# MLA q up-projection epilogue: eight RS loads issued together; 7 load+vmcnt(0) pairs that drained the previous group's stores removed
# speedup vs baseline: 1.0007x; 1.0007x over previous
;   __device__ __forceinline__ void operator()(const Acc& acc, int brow, int bcol, int wr, int wc, int fr, int fq) const {
;     ...
;         const int r = brow + 128 * ai + 64 * wr + 16 * m + fr;
;         const float rstd = rsqrtf(RS[2 * r] * (1.f / 256.f) + 1e-6f) * QSCALE;
;         int b, key; row_bk(r, b, key);
;         const bool latent = r >= NCTX;
;         const int t = (r - NCTX) & 8191;
;         bf16_t* qrow = Qall + ((size_t)(b * 8) * NKEY + key) * 96 + 4 * fq;
; #pragma unroll
;         for (int bj = 0; bj < 2; ++bj) {
;           const int c32 = bcol + 128 * bj + 32 * wc;
;           const int h = c32 / 96, d32 = c32 - 96 * h;
; #pragma unroll
;           for (int n = 0; n < 2; ++n) {
;             f32x4 v = acc[ai][bj][m][n] * rstd;
;             if (d32 == 64) {
;               f32x4 pv;
; #pragma unroll
;               for (int j = 0; j < 4; ++j) pv[j] = __shfl_xor(v[j], 32);
;               if (latent) {
;                 const float* rp = rope + ((size_t)t * 2 + n) * 16 + 4 * (fq & 1);
;                 const f32x4 cs = *(const f32x4*)rp, sn = *(const f32x4*)(rp + 8);
;                 v = (fq < 2) ? (v * cs - pv * sn) : (pv * sn + v * cs);
.LBB0_997:
	s_and_b64 vcc, exec, s[0:1]
	s_cbranch_vccz .LBB0_821
	global_load_dword v149, v[150:151], off
	global_load_dword v236, v[150:151], off offset:128
	global_load_dword v237, v[150:151], off offset:256
	global_load_dword v238, v[150:151], off offset:384
	global_load_dword v239, v[150:151], off offset:1024
	global_load_dword v240, v[150:151], off offset:1152
	global_load_dword v241, v[150:151], off offset:1280
	global_load_dword v242, v[150:151], off offset:1408
	v_cmp_lt_i32_e32 vcc, s67, v173
	s_and_saveexec_b64 s[0:1], vcc
	s_xor_b64 s[0:1], exec, s[0:1]
	v_add_u32_e32 v132, 0xfffffc00, v173
	v_lshrrev_b32_e32 v154, 13, v132
	v_and_b32_e32 v132, 0x1fcf, v132
	v_add_u32_e32 v132, 0x100, v132
	s_andn2_saveexec_b64 s[0:1], s[0:1]
	s_ashr_i32 s3, s4, 8
	v_and_b32_e32 v132, 0xcf, v173
	v_mov_b32_e32 v154, s3
	s_or_b64 exec, exec, s[0:1]
	s_waitcnt vmcnt(0)
	v_fmamk_f32 v149, v149, 0x3b800000, v169
	v_mul_f32_e32 v150, 0x4b800000, v149
	v_cmp_gt_f32_e32 vcc, s68, v149
	s_or_b32 s10, s2, s60
	s_mul_hi_i32 s0, s10, 0x2aaaaaab
	v_cndmask_b32_e32 v149, v149, v150, vcc
	v_rsq_f32_e32 v149, v149
	s_lshr_b32 s1, s0, 31
	s_ashr_i32 s5, s0, 4
	s_add_i32 s5, s5, s1
	v_mul_f32_e32 v150, 0x45800000, v149
	s_mul_i32 s0, s5, 0xffffffa0
	v_cndmask_b32_e32 v149, v149, v150, vcc
	s_add_i32 s44, s0, s10
	v_mul_f32_e32 v150, 0x3e16c740, v149
	v_add_u32_e32 v148, 0x3800, v148
	s_cmp_eq_u32 s44, 64
	v_cmp_lt_i32_e64 s[12:13], s67, v173
	v_and_b32_e32 v156, 0x3f9e, v148
	s_cselect_b64 s[0:1], -1, 0
	s_cmp_lg_u32 s44, 64
	v_pk_mul_f32 v[126:127], v[126:127], v[150:151] op_sel_hi:[1,0]
	v_pk_mul_f32 v[152:153], v[124:125], v[150:151] op_sel_hi:[1,0]
	s_cbranch_scc1 .LBB0_1006
	v_and_b32_e32 v125, 64, v172
	v_xor_b32_e32 v124, 32, v172
	v_add_u32_e32 v125, 64, v125
	v_cmp_lt_i32_e32 vcc, v124, v125
	s_nop 1
	v_cndmask_b32_e32 v124, v172, v124, vcc
	v_lshlrev_b32_e32 v149, 2, v124
	ds_bpermute_b32 v124, v149, v152
	ds_bpermute_b32 v125, v149, v153
	ds_bpermute_b32 v148, v149, v126
	ds_bpermute_b32 v149, v149, v127
	s_and_saveexec_b64 s[2:3], s[12:13]
	s_cbranch_execz .LBB0_1005
	v_lshlrev_b32_e32 v158, 6, v156
	v_mov_b32_e32 v159, v133
	v_lshl_add_u64 v[162:163], v[140:141], 0, v[158:159]
	global_load_dwordx4 v[158:161], v[162:163], off offset:32
	global_load_dwordx4 v[180:183], v[162:163], off
	s_waitcnt vmcnt(0) lgkmcnt(0)
	v_pk_mul_f32 v[148:149], v[160:161], v[148:149]
	v_pk_mul_f32 v[124:125], v[158:159], v[124:125]
	v_xor_b32_e32 v157, 0x80000000, v148
	v_xor_b32_e32 v151, 0x80000000, v124
	v_xor_b32_e32 v155, 0x80000000, v125
	v_xor_b32_e32 v158, 0x80000000, v149
	v_cndmask_b32_e64 v149, v149, v158, s[6:7]
	v_cndmask_b32_e64 v148, v148, v157, s[6:7]
	v_cndmask_b32_e64 v125, v125, v155, s[6:7]
	v_cndmask_b32_e64 v124, v124, v151, s[6:7]
	v_pk_fma_f32 v[152:153], v[152:153], v[180:181], v[124:125]
	v_pk_fma_f32 v[126:127], v[126:127], v[182:183], v[148:149]

; __device__ __forceinline__ unsigned pk2(float lo, float hi) { f32x2 v = {lo, hi}; return __builtin_bit_cast(unsigned, __builtin_convertvector(v, bf16v2)); }
;   __device__ __forceinline__ void operator()(const Acc& acc, int brow, int bcol, int wr, int wc, int fr, int fq) const {
;     ...
;         const int r = brow + 128 * ai + 64 * wr + 16 * m + fr;
;         const float rstd = rsqrtf(RS[2 * r] * (1.f / 256.f) + 1e-6f) * QSCALE;
;         int b, key; row_bk(r, b, key);
;     ...
;             u32x2 o; o.x = pk2(v[0], v[1]); o.y = pk2(v[2], v[3]);
;             *(u32x2*)(qrow + (size_t)h * (NKEY * 96) + d32 + 16 * n) = o;
.LBB0_1018:
	v_cvt_pk_bf16_f32 v112, v112, v113
	v_cvt_pk_bf16_f32 v113, v114, v115
	v_or_b32_e32 v114, 16, v173
	global_store_dwordx2 v[116:117], v[112:113], off offset:32
	v_lshlrev_b32_e32 v112, 1, v114
	v_ashrrev_i32_e32 v113, 31, v112
	v_lshl_add_u64 v[116:117], v[112:113], 2, s[16:17]
	v_mov_b32_e32 v113, v236
	v_cmp_lt_i32_e32 vcc, s67, v114
	s_and_saveexec_b64 s[0:1], vcc
	s_xor_b64 s[0:1], exec, s[0:1]
	s_cbranch_execz .LBB0_1020
	v_add_u32_e32 v115, 0xfffffc10, v173
	s_waitcnt lgkmcnt(3)
	v_lshrrev_b32_e32 v118, 13, v115
	v_and_b32_e32 v115, 0x1fdf, v115
	v_add_u32_e32 v132, 0x100, v115

;   __device__ __forceinline__ void operator()(const Acc& acc, int brow, int bcol, int wr, int wc, int fr, int fq) const {
;     ...
;         const float rstd = rsqrtf(RS[2 * r] * (1.f / 256.f) + 1e-6f) * QSCALE;
;         int b, key; row_bk(r, b, key);
;         const bool latent = r >= NCTX;
;         const int t = (r - NCTX) & 8191;
;         bf16_t* qrow = Qall + ((size_t)(b * 8) * NKEY + key) * 96 + 4 * fq;
; #pragma unroll
;         for (int bj = 0; bj < 2; ++bj) {
;           const int c32 = bcol + 128 * bj + 32 * wc;
;           const int h = c32 / 96, d32 = c32 - 96 * h;
; #pragma unroll
;           for (int n = 0; n < 2; ++n) {
;             f32x4 v = acc[ai][bj][m][n] * rstd;
;             if (d32 == 64) {
;               f32x4 pv;
; #pragma unroll
;               for (int j = 0; j < 4; ++j) pv[j] = __shfl_xor(v[j], 32);
;               if (latent) {
;                 const float* rp = rope + ((size_t)t * 2 + n) * 16 + 4 * (fq & 1);
;                 const f32x4 cs = *(const f32x4*)rp, sn = *(const f32x4*)(rp + 8);
;                 v = (fq < 2) ? (v * cs - pv * sn) : (pv * sn + v * cs);
.LBB0_1022:
	s_or_b64 exec, exec, s[0:1]
	v_fmamk_f32 v113, v113, 0x3b800000, v169
	v_mul_f32_e32 v115, 0x4b800000, v113
	v_cmp_gt_f32_e32 vcc, s68, v113
	v_cmp_lt_i32_e64 s[12:13], s67, v114
	v_add_u32_e32 v114, 0x3800, v112
	v_cndmask_b32_e32 v113, v113, v115, vcc
	v_rsq_f32_e32 v113, v113
	s_waitcnt lgkmcnt(1)
	v_and_b32_e32 v120, 0x3ffe, v114
	v_mul_f32_e32 v112, 0x45800000, v113
	v_cndmask_b32_e32 v112, v113, v112, vcc
	v_mul_f32_e32 v112, 0x3e16c740, v112
	v_pk_mul_f32 v[110:111], v[110:111], v[112:113] op_sel_hi:[1,0]
	s_and_b64 vcc, exec, s[8:9]
	v_pk_mul_f32 v[116:117], v[108:109], v[112:113] op_sel_hi:[1,0]
	s_cbranch_vccnz .LBB0_1026
	v_and_b32_e32 v109, 64, v172
	v_xor_b32_e32 v108, 32, v172
	v_add_u32_e32 v109, 64, v109
	v_cmp_lt_i32_e32 vcc, v108, v109
	s_nop 1
	v_cndmask_b32_e32 v108, v172, v108, vcc
	v_lshlrev_b32_e32 v113, 2, v108
	ds_bpermute_b32 v108, v113, v116
	ds_bpermute_b32 v109, v113, v117
	ds_bpermute_b32 v114, v113, v110
	ds_bpermute_b32 v115, v113, v111
	s_and_saveexec_b64 s[0:1], s[12:13]
	s_cbranch_execz .LBB0_1025
	v_lshlrev_b32_e32 v122, 6, v120
	s_waitcnt lgkmcnt(4)
	v_mov_b32_e32 v123, v133
	v_lshl_add_u64 v[126:127], v[140:141], 0, v[122:123]
	global_load_dwordx4 v[122:125], v[126:127], off offset:32
	global_load_dwordx4 v[148:151], v[126:127], off
	s_waitcnt vmcnt(1) lgkmcnt(0)
	v_pk_mul_f32 v[114:115], v[124:125], v[114:115]
	v_pk_mul_f32 v[108:109], v[122:123], v[108:109]
	v_xor_b32_e32 v121, 0x80000000, v114
	v_xor_b32_e32 v113, 0x80000000, v108
	v_xor_b32_e32 v119, 0x80000000, v109
	v_xor_b32_e32 v122, 0x80000000, v115
	v_cndmask_b32_e64 v115, v115, v122, s[6:7]
	v_cndmask_b32_e64 v114, v114, v121, s[6:7]
	v_cndmask_b32_e64 v109, v109, v119, s[6:7]
	v_cndmask_b32_e64 v108, v108, v113, s[6:7]
	s_waitcnt vmcnt(0)
	v_pk_fma_f32 v[116:117], v[116:117], v[148:149], v[108:109]
	v_pk_fma_f32 v[110:111], v[110:111], v[150:151], v[114:115]

; __device__ __forceinline__ unsigned pk2(float lo, float hi) { f32x2 v = {lo, hi}; return __builtin_bit_cast(unsigned, __builtin_convertvector(v, bf16v2)); }
;   __device__ __forceinline__ void operator()(const Acc& acc, int brow, int bcol, int wr, int wc, int fr, int fq) const {
;     ...
;         const int r = brow + 128 * ai + 64 * wr + 16 * m + fr;
;         const float rstd = rsqrtf(RS[2 * r] * (1.f / 256.f) + 1e-6f) * QSCALE;
;         int b, key; row_bk(r, b, key);
;     ...
;             u32x2 o; o.x = pk2(v[0], v[1]); o.y = pk2(v[2], v[3]);
;             *(u32x2*)(qrow + (size_t)h * (NKEY * 96) + d32 + 16 * n) = o;
.LBB0_1038:
	v_cvt_pk_bf16_f32 v96, v96, v97
	v_cvt_pk_bf16_f32 v97, v98, v99
	v_or_b32_e32 v98, 32, v173
	global_store_dwordx2 v[100:101], v[96:97], off offset:32
	v_lshlrev_b32_e32 v96, 1, v98
	v_ashrrev_i32_e32 v97, 31, v96
	v_lshl_add_u64 v[100:101], v[96:97], 2, s[16:17]
	v_mov_b32_e32 v97, v237
	v_cmp_lt_i32_e32 vcc, s67, v98
	s_and_saveexec_b64 s[0:1], vcc
	s_xor_b64 s[0:1], exec, s[0:1]
	s_cbranch_execz .LBB0_1040
	v_add_u32_e32 v99, 0xfffffc20, v173
	s_waitcnt lgkmcnt(3)
	v_lshrrev_b32_e32 v102, 13, v99
	v_and_b32_e32 v99, 0x1fef, v99
	v_add_u32_e32 v132, 0x100, v99

;   __device__ __forceinline__ void operator()(const Acc& acc, int brow, int bcol, int wr, int wc, int fr, int fq) const {
;     ...
;         const float rstd = rsqrtf(RS[2 * r] * (1.f / 256.f) + 1e-6f) * QSCALE;
;         int b, key; row_bk(r, b, key);
;         const bool latent = r >= NCTX;
;         const int t = (r - NCTX) & 8191;
;         bf16_t* qrow = Qall + ((size_t)(b * 8) * NKEY + key) * 96 + 4 * fq;
; #pragma unroll
;         for (int bj = 0; bj < 2; ++bj) {
;           const int c32 = bcol + 128 * bj + 32 * wc;
;           const int h = c32 / 96, d32 = c32 - 96 * h;
; #pragma unroll
;           for (int n = 0; n < 2; ++n) {
;             f32x4 v = acc[ai][bj][m][n] * rstd;
;             if (d32 == 64) {
;               f32x4 pv;
; #pragma unroll
;               for (int j = 0; j < 4; ++j) pv[j] = __shfl_xor(v[j], 32);
;               if (latent) {
;                 const float* rp = rope + ((size_t)t * 2 + n) * 16 + 4 * (fq & 1);
;                 const f32x4 cs = *(const f32x4*)rp, sn = *(const f32x4*)(rp + 8);
;                 v = (fq < 2) ? (v * cs - pv * sn) : (pv * sn + v * cs);
.LBB0_1042:
	s_or_b64 exec, exec, s[0:1]
	v_fmamk_f32 v97, v97, 0x3b800000, v169
	v_mul_f32_e32 v99, 0x4b800000, v97
	v_cmp_gt_f32_e32 vcc, s68, v97
	v_cmp_lt_i32_e64 s[12:13], s67, v98
	v_add_u32_e32 v98, 0x3800, v96
	v_cndmask_b32_e32 v97, v97, v99, vcc
	v_rsq_f32_e32 v97, v97
	s_waitcnt lgkmcnt(1)
	v_and_b32_e32 v104, 0x3ffe, v98
	v_mul_f32_e32 v96, 0x45800000, v97
	v_cndmask_b32_e32 v96, v97, v96, vcc
	v_mul_f32_e32 v96, 0x3e16c740, v96
	v_pk_mul_f32 v[98:99], v[94:95], v[96:97] op_sel_hi:[1,0]
	s_and_b64 vcc, exec, s[8:9]
	v_pk_mul_f32 v[100:101], v[92:93], v[96:97] op_sel_hi:[1,0]
	s_cbranch_vccnz .LBB0_1046
	v_and_b32_e32 v93, 64, v172
	v_xor_b32_e32 v92, 32, v172
	v_add_u32_e32 v93, 64, v93
	v_cmp_lt_i32_e32 vcc, v92, v93
	s_nop 1
	v_cndmask_b32_e32 v92, v172, v92, vcc
	v_lshlrev_b32_e32 v95, 2, v92
	ds_bpermute_b32 v92, v95, v100
	ds_bpermute_b32 v93, v95, v101
	ds_bpermute_b32 v94, v95, v98
	ds_bpermute_b32 v95, v95, v99
	s_and_saveexec_b64 s[0:1], s[12:13]
	s_cbranch_execz .LBB0_1045
	v_lshlrev_b32_e32 v106, 6, v104
	s_waitcnt lgkmcnt(4)
	v_mov_b32_e32 v107, v133
	v_lshl_add_u64 v[110:111], v[140:141], 0, v[106:107]
	global_load_dwordx4 v[106:109], v[110:111], off offset:32
	s_nop 0
	global_load_dwordx4 v[110:113], v[110:111], off
	s_waitcnt vmcnt(1) lgkmcnt(0)
	v_pk_mul_f32 v[94:95], v[108:109], v[94:95]
	v_pk_mul_f32 v[92:93], v[106:107], v[92:93]
	v_xor_b32_e32 v105, 0x80000000, v94
	v_xor_b32_e32 v97, 0x80000000, v92
	v_xor_b32_e32 v103, 0x80000000, v93
	v_xor_b32_e32 v106, 0x80000000, v95
	v_cndmask_b32_e64 v95, v95, v106, s[6:7]
	v_cndmask_b32_e64 v94, v94, v105, s[6:7]
	v_cndmask_b32_e64 v93, v93, v103, s[6:7]
	v_cndmask_b32_e64 v92, v92, v97, s[6:7]
	s_waitcnt vmcnt(0)
	v_pk_fma_f32 v[100:101], v[100:101], v[110:111], v[92:93]
	v_pk_fma_f32 v[98:99], v[98:99], v[112:113], v[94:95]

; __device__ __forceinline__ unsigned pk2(float lo, float hi) { f32x2 v = {lo, hi}; return __builtin_bit_cast(unsigned, __builtin_convertvector(v, bf16v2)); }
;   __device__ __forceinline__ void operator()(const Acc& acc, int brow, int bcol, int wr, int wc, int fr, int fq) const {
;     ...
;         const int r = brow + 128 * ai + 64 * wr + 16 * m + fr;
;         const float rstd = rsqrtf(RS[2 * r] * (1.f / 256.f) + 1e-6f) * QSCALE;
;         int b, key; row_bk(r, b, key);
;     ...
;             u32x2 o; o.x = pk2(v[0], v[1]); o.y = pk2(v[2], v[3]);
;             *(u32x2*)(qrow + (size_t)h * (NKEY * 96) + d32 + 16 * n) = o;
.LBB0_1058:
	v_cvt_pk_bf16_f32 v80, v80, v81
	v_cvt_pk_bf16_f32 v81, v82, v83
	v_or_b32_e32 v82, 48, v173
	global_store_dwordx2 v[84:85], v[80:81], off offset:32
	v_lshlrev_b32_e32 v80, 1, v82
	v_ashrrev_i32_e32 v81, 31, v80
	v_lshl_add_u64 v[84:85], v[80:81], 2, s[16:17]
	v_mov_b32_e32 v81, v238
	v_cmp_lt_i32_e32 vcc, s67, v82
	s_and_saveexec_b64 s[0:1], vcc
	s_xor_b64 s[0:1], exec, s[0:1]
	s_cbranch_execz .LBB0_1060
	v_add_u32_e32 v83, 0xfffffc30, v173
	s_waitcnt lgkmcnt(3)
	v_lshrrev_b32_e32 v86, 13, v83
	v_and_b32_e32 v83, 0x1fff, v83
	v_add_u32_e32 v132, 0x100, v83

;   __device__ __forceinline__ void operator()(const Acc& acc, int brow, int bcol, int wr, int wc, int fr, int fq) const {
;     ...
;         const float rstd = rsqrtf(RS[2 * r] * (1.f / 256.f) + 1e-6f) * QSCALE;
;         int b, key; row_bk(r, b, key);
;         const bool latent = r >= NCTX;
;         const int t = (r - NCTX) & 8191;
;         bf16_t* qrow = Qall + ((size_t)(b * 8) * NKEY + key) * 96 + 4 * fq;
; #pragma unroll
;         for (int bj = 0; bj < 2; ++bj) {
;           const int c32 = bcol + 128 * bj + 32 * wc;
;           const int h = c32 / 96, d32 = c32 - 96 * h;
; #pragma unroll
;           for (int n = 0; n < 2; ++n) {
;             f32x4 v = acc[ai][bj][m][n] * rstd;
;             if (d32 == 64) {
;               f32x4 pv;
; #pragma unroll
;               for (int j = 0; j < 4; ++j) pv[j] = __shfl_xor(v[j], 32);
;               if (latent) {
;                 const float* rp = rope + ((size_t)t * 2 + n) * 16 + 4 * (fq & 1);
;                 const f32x4 cs = *(const f32x4*)rp, sn = *(const f32x4*)(rp + 8);
;                 v = (fq < 2) ? (v * cs - pv * sn) : (pv * sn + v * cs);
.LBB0_1062:
	s_or_b64 exec, exec, s[0:1]
	v_fmamk_f32 v81, v81, 0x3b800000, v169
	v_mul_f32_e32 v83, 0x4b800000, v81
	v_cmp_gt_f32_e32 vcc, s68, v81
	v_cmp_lt_i32_e64 s[12:13], s67, v82
	v_add_u32_e32 v82, 0x3800, v80
	v_cndmask_b32_e32 v81, v81, v83, vcc
	v_rsq_f32_e32 v81, v81
	s_waitcnt lgkmcnt(1)
	v_and_b32_e32 v88, 0x3ffe, v82
	v_mul_f32_e32 v80, 0x45800000, v81
	v_cndmask_b32_e32 v80, v81, v80, vcc
	v_mul_f32_e32 v80, 0x3e16c740, v80
	v_pk_mul_f32 v[82:83], v[78:79], v[80:81] op_sel_hi:[1,0]
	s_and_b64 vcc, exec, s[8:9]
	v_pk_mul_f32 v[84:85], v[76:77], v[80:81] op_sel_hi:[1,0]
	s_cbranch_vccnz .LBB0_1066
	v_and_b32_e32 v77, 64, v172
	v_xor_b32_e32 v76, 32, v172
	v_add_u32_e32 v77, 64, v77
	v_cmp_lt_i32_e32 vcc, v76, v77
	s_nop 1
	v_cndmask_b32_e32 v76, v172, v76, vcc
	v_lshlrev_b32_e32 v79, 2, v76
	ds_bpermute_b32 v76, v79, v84
	ds_bpermute_b32 v77, v79, v85
	ds_bpermute_b32 v78, v79, v82
	ds_bpermute_b32 v79, v79, v83
	s_and_saveexec_b64 s[0:1], s[12:13]
	s_cbranch_execz .LBB0_1065
	v_lshlrev_b32_e32 v90, 6, v88
	s_waitcnt lgkmcnt(4)
	v_mov_b32_e32 v91, v133
	v_lshl_add_u64 v[94:95], v[140:141], 0, v[90:91]
	global_load_dwordx4 v[90:93], v[94:95], off offset:32
	s_nop 0
	global_load_dwordx4 v[94:97], v[94:95], off
	s_waitcnt vmcnt(1) lgkmcnt(0)
	v_pk_mul_f32 v[78:79], v[92:93], v[78:79]
	v_pk_mul_f32 v[76:77], v[90:91], v[76:77]
	v_xor_b32_e32 v89, 0x80000000, v78
	v_xor_b32_e32 v81, 0x80000000, v76
	v_xor_b32_e32 v87, 0x80000000, v77
	v_xor_b32_e32 v90, 0x80000000, v79
	v_cndmask_b32_e64 v79, v79, v90, s[6:7]
	v_cndmask_b32_e64 v78, v78, v89, s[6:7]
	v_cndmask_b32_e64 v77, v77, v87, s[6:7]
	v_cndmask_b32_e64 v76, v76, v81, s[6:7]
	s_waitcnt vmcnt(0)
	v_pk_fma_f32 v[84:85], v[84:85], v[94:95], v[76:77]
	v_pk_fma_f32 v[82:83], v[82:83], v[96:97], v[78:79]

; __device__ __forceinline__ unsigned pk2(float lo, float hi) { f32x2 v = {lo, hi}; return __builtin_bit_cast(unsigned, __builtin_convertvector(v, bf16v2)); }
;   __device__ __forceinline__ void operator()(const Acc& acc, int brow, int bcol, int wr, int wc, int fr, int fq) const {
;     ...
;         const int r = brow + 128 * ai + 64 * wr + 16 * m + fr;
;         const float rstd = rsqrtf(RS[2 * r] * (1.f / 256.f) + 1e-6f) * QSCALE;
;         int b, key; row_bk(r, b, key);
;     ...
;             u32x2 o; o.x = pk2(v[0], v[1]); o.y = pk2(v[2], v[3]);
;             *(u32x2*)(qrow + (size_t)h * (NKEY * 96) + d32 + 16 * n) = o;
.LBB0_1078:
	v_cvt_pk_bf16_f32 v64, v64, v65
	v_cvt_pk_bf16_f32 v65, v66, v67
	v_add_u32_e32 v66, 0x80, v173
	global_store_dwordx2 v[68:69], v[64:65], off offset:32
	v_lshlrev_b32_e32 v64, 1, v66
	v_ashrrev_i32_e32 v65, 31, v64
	v_lshl_add_u64 v[68:69], v[64:65], 2, s[16:17]
	v_mov_b32_e32 v65, v239
	v_cmp_lt_i32_e32 vcc, s67, v66
	s_and_saveexec_b64 s[0:1], vcc
	s_xor_b64 s[0:1], exec, s[0:1]
	s_cbranch_execz .LBB0_1080
	v_add_u32_e32 v67, 0xfffffc80, v173
	s_waitcnt lgkmcnt(3)
	v_lshrrev_b32_e32 v70, 13, v67
	v_and_b32_e32 v67, 0x1fcf, v67
	v_add_u32_e32 v132, 0x100, v67

;   __device__ __forceinline__ void operator()(const Acc& acc, int brow, int bcol, int wr, int wc, int fr, int fq) const {
;     ...
;         const float rstd = rsqrtf(RS[2 * r] * (1.f / 256.f) + 1e-6f) * QSCALE;
;         int b, key; row_bk(r, b, key);
;         const bool latent = r >= NCTX;
;         const int t = (r - NCTX) & 8191;
;         bf16_t* qrow = Qall + ((size_t)(b * 8) * NKEY + key) * 96 + 4 * fq;
; #pragma unroll
;         for (int bj = 0; bj < 2; ++bj) {
;           const int c32 = bcol + 128 * bj + 32 * wc;
;           const int h = c32 / 96, d32 = c32 - 96 * h;
; #pragma unroll
;           for (int n = 0; n < 2; ++n) {
;             f32x4 v = acc[ai][bj][m][n] * rstd;
;             if (d32 == 64) {
;               f32x4 pv;
; #pragma unroll
;               for (int j = 0; j < 4; ++j) pv[j] = __shfl_xor(v[j], 32);
;               if (latent) {
;                 const float* rp = rope + ((size_t)t * 2 + n) * 16 + 4 * (fq & 1);
;                 const f32x4 cs = *(const f32x4*)rp, sn = *(const f32x4*)(rp + 8);
;                 v = (fq < 2) ? (v * cs - pv * sn) : (pv * sn + v * cs);
.LBB0_1082:
	s_or_b64 exec, exec, s[0:1]
	v_fmamk_f32 v65, v65, 0x3b800000, v169
	v_mul_f32_e32 v67, 0x4b800000, v65
	v_cmp_gt_f32_e32 vcc, s68, v65
	v_cmp_lt_i32_e64 s[12:13], s67, v66
	v_add_u32_e32 v66, 0x3800, v64
	v_cndmask_b32_e32 v65, v65, v67, vcc
	v_rsq_f32_e32 v65, v65
	s_waitcnt lgkmcnt(1)
	v_and_b32_e32 v72, 0x3ffe, v66
	v_mul_f32_e32 v64, 0x45800000, v65
	v_cndmask_b32_e32 v64, v65, v64, vcc
	v_mul_f32_e32 v64, 0x3e16c740, v64
	v_pk_mul_f32 v[66:67], v[62:63], v[64:65] op_sel_hi:[1,0]
	s_and_b64 vcc, exec, s[8:9]
	v_pk_mul_f32 v[68:69], v[60:61], v[64:65] op_sel_hi:[1,0]
	s_cbranch_vccnz .LBB0_1086
	v_and_b32_e32 v61, 64, v172
	v_xor_b32_e32 v60, 32, v172
	v_add_u32_e32 v61, 64, v61
	v_cmp_lt_i32_e32 vcc, v60, v61
	s_nop 1
	v_cndmask_b32_e32 v60, v172, v60, vcc
	v_lshlrev_b32_e32 v63, 2, v60
	ds_bpermute_b32 v60, v63, v68
	ds_bpermute_b32 v61, v63, v69
	ds_bpermute_b32 v62, v63, v66
	ds_bpermute_b32 v63, v63, v67
	s_and_saveexec_b64 s[0:1], s[12:13]
	s_cbranch_execz .LBB0_1085
	v_lshlrev_b32_e32 v74, 6, v72
	s_waitcnt lgkmcnt(4)
	v_mov_b32_e32 v75, v133
	v_lshl_add_u64 v[78:79], v[140:141], 0, v[74:75]
	global_load_dwordx4 v[74:77], v[78:79], off offset:32
	s_nop 0
	global_load_dwordx4 v[78:81], v[78:79], off
	s_waitcnt vmcnt(1) lgkmcnt(0)
	v_pk_mul_f32 v[62:63], v[76:77], v[62:63]
	v_pk_mul_f32 v[60:61], v[74:75], v[60:61]
	v_xor_b32_e32 v73, 0x80000000, v62
	v_xor_b32_e32 v65, 0x80000000, v60
	v_xor_b32_e32 v71, 0x80000000, v61
	v_xor_b32_e32 v74, 0x80000000, v63
	v_cndmask_b32_e64 v63, v63, v74, s[6:7]
	v_cndmask_b32_e64 v62, v62, v73, s[6:7]
	v_cndmask_b32_e64 v61, v61, v71, s[6:7]
	v_cndmask_b32_e64 v60, v60, v65, s[6:7]
	s_waitcnt vmcnt(0)
	v_pk_fma_f32 v[68:69], v[68:69], v[78:79], v[60:61]
	v_pk_fma_f32 v[66:67], v[66:67], v[80:81], v[62:63]

; __device__ __forceinline__ unsigned pk2(float lo, float hi) { f32x2 v = {lo, hi}; return __builtin_bit_cast(unsigned, __builtin_convertvector(v, bf16v2)); }
;   __device__ __forceinline__ void operator()(const Acc& acc, int brow, int bcol, int wr, int wc, int fr, int fq) const {
;     ...
;         const int r = brow + 128 * ai + 64 * wr + 16 * m + fr;
;         const float rstd = rsqrtf(RS[2 * r] * (1.f / 256.f) + 1e-6f) * QSCALE;
;         int b, key; row_bk(r, b, key);
;     ...
;             u32x2 o; o.x = pk2(v[0], v[1]); o.y = pk2(v[2], v[3]);
;             *(u32x2*)(qrow + (size_t)h * (NKEY * 96) + d32 + 16 * n) = o;
.LBB0_1098:
	v_cvt_pk_bf16_f32 v48, v48, v49
	v_cvt_pk_bf16_f32 v49, v50, v51
	v_add_u32_e32 v50, 0x90, v173
	global_store_dwordx2 v[52:53], v[48:49], off offset:32
	v_lshlrev_b32_e32 v48, 1, v50
	v_ashrrev_i32_e32 v49, 31, v48
	v_lshl_add_u64 v[52:53], v[48:49], 2, s[16:17]
	v_mov_b32_e32 v49, v240
	v_cmp_lt_i32_e32 vcc, s67, v50
	s_and_saveexec_b64 s[0:1], vcc
	s_xor_b64 s[0:1], exec, s[0:1]
	s_cbranch_execz .LBB0_1100
	v_add_u32_e32 v51, 0xfffffc90, v173
	s_waitcnt lgkmcnt(3)
	v_lshrrev_b32_e32 v54, 13, v51
	v_and_b32_e32 v51, 0x1fdf, v51
	v_add_u32_e32 v132, 0x100, v51

;   __device__ __forceinline__ void operator()(const Acc& acc, int brow, int bcol, int wr, int wc, int fr, int fq) const {
;     ...
;         const float rstd = rsqrtf(RS[2 * r] * (1.f / 256.f) + 1e-6f) * QSCALE;
;         int b, key; row_bk(r, b, key);
;         const bool latent = r >= NCTX;
;         const int t = (r - NCTX) & 8191;
;         bf16_t* qrow = Qall + ((size_t)(b * 8) * NKEY + key) * 96 + 4 * fq;
; #pragma unroll
;         for (int bj = 0; bj < 2; ++bj) {
;           const int c32 = bcol + 128 * bj + 32 * wc;
;           const int h = c32 / 96, d32 = c32 - 96 * h;
; #pragma unroll
;           for (int n = 0; n < 2; ++n) {
;             f32x4 v = acc[ai][bj][m][n] * rstd;
;             if (d32 == 64) {
;               f32x4 pv;
; #pragma unroll
;               for (int j = 0; j < 4; ++j) pv[j] = __shfl_xor(v[j], 32);
;               if (latent) {
;                 const float* rp = rope + ((size_t)t * 2 + n) * 16 + 4 * (fq & 1);
;                 const f32x4 cs = *(const f32x4*)rp, sn = *(const f32x4*)(rp + 8);
;                 v = (fq < 2) ? (v * cs - pv * sn) : (pv * sn + v * cs);
.LBB0_1102:
	s_or_b64 exec, exec, s[0:1]
	v_fmamk_f32 v49, v49, 0x3b800000, v169
	v_mul_f32_e32 v51, 0x4b800000, v49
	v_cmp_gt_f32_e32 vcc, s68, v49
	v_cmp_lt_i32_e64 s[12:13], s67, v50
	v_add_u32_e32 v50, 0x3800, v48
	v_cndmask_b32_e32 v49, v49, v51, vcc
	v_rsq_f32_e32 v49, v49
	s_waitcnt lgkmcnt(1)
	v_and_b32_e32 v56, 0x3ffe, v50
	v_mul_f32_e32 v48, 0x45800000, v49
	v_cndmask_b32_e32 v48, v49, v48, vcc
	v_mul_f32_e32 v48, 0x3e16c740, v48
	v_pk_mul_f32 v[50:51], v[46:47], v[48:49] op_sel_hi:[1,0]
	s_and_b64 vcc, exec, s[8:9]
	v_pk_mul_f32 v[52:53], v[44:45], v[48:49] op_sel_hi:[1,0]
	s_cbranch_vccnz .LBB0_1106
	v_and_b32_e32 v45, 64, v172
	v_xor_b32_e32 v44, 32, v172
	v_add_u32_e32 v45, 64, v45
	v_cmp_lt_i32_e32 vcc, v44, v45
	s_nop 1
	v_cndmask_b32_e32 v44, v172, v44, vcc
	v_lshlrev_b32_e32 v47, 2, v44
	ds_bpermute_b32 v44, v47, v52
	ds_bpermute_b32 v45, v47, v53
	ds_bpermute_b32 v46, v47, v50
	ds_bpermute_b32 v47, v47, v51
	s_and_saveexec_b64 s[0:1], s[12:13]
	s_cbranch_execz .LBB0_1105
	v_lshlrev_b32_e32 v58, 6, v56
	s_waitcnt lgkmcnt(4)
	v_mov_b32_e32 v59, v133
	v_lshl_add_u64 v[62:63], v[140:141], 0, v[58:59]
	global_load_dwordx4 v[58:61], v[62:63], off offset:32
	s_nop 0
	global_load_dwordx4 v[62:65], v[62:63], off
	s_waitcnt vmcnt(1) lgkmcnt(0)
	v_pk_mul_f32 v[46:47], v[60:61], v[46:47]
	v_pk_mul_f32 v[44:45], v[58:59], v[44:45]
	v_xor_b32_e32 v57, 0x80000000, v46
	v_xor_b32_e32 v49, 0x80000000, v44
	v_xor_b32_e32 v55, 0x80000000, v45
	v_xor_b32_e32 v58, 0x80000000, v47
	v_cndmask_b32_e64 v47, v47, v58, s[6:7]
	v_cndmask_b32_e64 v46, v46, v57, s[6:7]
	v_cndmask_b32_e64 v45, v45, v55, s[6:7]
	v_cndmask_b32_e64 v44, v44, v49, s[6:7]
	s_waitcnt vmcnt(0)
	v_pk_fma_f32 v[52:53], v[52:53], v[62:63], v[44:45]
	v_pk_fma_f32 v[50:51], v[50:51], v[64:65], v[46:47]

; __device__ __forceinline__ unsigned pk2(float lo, float hi) { f32x2 v = {lo, hi}; return __builtin_bit_cast(unsigned, __builtin_convertvector(v, bf16v2)); }
;   __device__ __forceinline__ void operator()(const Acc& acc, int brow, int bcol, int wr, int wc, int fr, int fq) const {
;     ...
;         const int r = brow + 128 * ai + 64 * wr + 16 * m + fr;
;         const float rstd = rsqrtf(RS[2 * r] * (1.f / 256.f) + 1e-6f) * QSCALE;
;         int b, key; row_bk(r, b, key);
;     ...
;             u32x2 o; o.x = pk2(v[0], v[1]); o.y = pk2(v[2], v[3]);
;             *(u32x2*)(qrow + (size_t)h * (NKEY * 96) + d32 + 16 * n) = o;
.LBB0_1118:
	v_cvt_pk_bf16_f32 v32, v32, v33
	v_cvt_pk_bf16_f32 v33, v34, v35
	v_add_u32_e32 v34, 0xa0, v173
	global_store_dwordx2 v[36:37], v[32:33], off offset:32
	v_lshlrev_b32_e32 v32, 1, v34
	v_ashrrev_i32_e32 v33, 31, v32
	v_lshl_add_u64 v[36:37], v[32:33], 2, s[16:17]
	v_mov_b32_e32 v33, v241
	v_cmp_lt_i32_e32 vcc, s67, v34
	s_and_saveexec_b64 s[0:1], vcc
	s_xor_b64 s[0:1], exec, s[0:1]
	s_cbranch_execz .LBB0_1120
	v_add_u32_e32 v35, 0xfffffca0, v173
	s_waitcnt lgkmcnt(3)
	v_lshrrev_b32_e32 v38, 13, v35
	v_and_b32_e32 v35, 0x1fef, v35
	v_add_u32_e32 v132, 0x100, v35

;   __device__ __forceinline__ void operator()(const Acc& acc, int brow, int bcol, int wr, int wc, int fr, int fq) const {
;     ...
;         const float rstd = rsqrtf(RS[2 * r] * (1.f / 256.f) + 1e-6f) * QSCALE;
;         int b, key; row_bk(r, b, key);
;         const bool latent = r >= NCTX;
;         const int t = (r - NCTX) & 8191;
;         bf16_t* qrow = Qall + ((size_t)(b * 8) * NKEY + key) * 96 + 4 * fq;
; #pragma unroll
;         for (int bj = 0; bj < 2; ++bj) {
;           const int c32 = bcol + 128 * bj + 32 * wc;
;           const int h = c32 / 96, d32 = c32 - 96 * h;
; #pragma unroll
;           for (int n = 0; n < 2; ++n) {
;             f32x4 v = acc[ai][bj][m][n] * rstd;
;             if (d32 == 64) {
;               f32x4 pv;
; #pragma unroll
;               for (int j = 0; j < 4; ++j) pv[j] = __shfl_xor(v[j], 32);
;               if (latent) {
;                 const float* rp = rope + ((size_t)t * 2 + n) * 16 + 4 * (fq & 1);
;                 const f32x4 cs = *(const f32x4*)rp, sn = *(const f32x4*)(rp + 8);
;                 v = (fq < 2) ? (v * cs - pv * sn) : (pv * sn + v * cs);
.LBB0_1122:
	s_or_b64 exec, exec, s[0:1]
	v_fmamk_f32 v33, v33, 0x3b800000, v169
	v_mul_f32_e32 v35, 0x4b800000, v33
	v_cmp_gt_f32_e32 vcc, s68, v33
	v_cmp_lt_i32_e64 s[12:13], s67, v34
	v_add_u32_e32 v34, 0x3800, v32
	v_cndmask_b32_e32 v33, v33, v35, vcc
	v_rsq_f32_e32 v33, v33
	s_waitcnt lgkmcnt(1)
	v_and_b32_e32 v40, 0x3ffe, v34
	v_mul_f32_e32 v32, 0x45800000, v33
	v_cndmask_b32_e32 v32, v33, v32, vcc
	v_mul_f32_e32 v32, 0x3e16c740, v32
	v_pk_mul_f32 v[34:35], v[30:31], v[32:33] op_sel_hi:[1,0]
	s_and_b64 vcc, exec, s[8:9]
	v_pk_mul_f32 v[36:37], v[28:29], v[32:33] op_sel_hi:[1,0]
	s_cbranch_vccnz .LBB0_1126
	v_and_b32_e32 v29, 64, v172
	v_xor_b32_e32 v28, 32, v172
	v_add_u32_e32 v29, 64, v29
	v_cmp_lt_i32_e32 vcc, v28, v29
	s_nop 1
	v_cndmask_b32_e32 v28, v172, v28, vcc
	v_lshlrev_b32_e32 v31, 2, v28
	ds_bpermute_b32 v28, v31, v36
	ds_bpermute_b32 v29, v31, v37
	ds_bpermute_b32 v30, v31, v34
	ds_bpermute_b32 v31, v31, v35
	s_and_saveexec_b64 s[0:1], s[12:13]
	s_cbranch_execz .LBB0_1125
	v_lshlrev_b32_e32 v42, 6, v40
	s_waitcnt lgkmcnt(4)
	v_mov_b32_e32 v43, v133
	v_lshl_add_u64 v[46:47], v[140:141], 0, v[42:43]
	global_load_dwordx4 v[42:45], v[46:47], off offset:32
	s_nop 0
	global_load_dwordx4 v[46:49], v[46:47], off
	s_waitcnt vmcnt(1) lgkmcnt(0)
	v_pk_mul_f32 v[30:31], v[44:45], v[30:31]
	v_pk_mul_f32 v[28:29], v[42:43], v[28:29]
	v_xor_b32_e32 v41, 0x80000000, v30
	v_xor_b32_e32 v33, 0x80000000, v28
	v_xor_b32_e32 v39, 0x80000000, v29
	v_xor_b32_e32 v42, 0x80000000, v31
	v_cndmask_b32_e64 v31, v31, v42, s[6:7]
	v_cndmask_b32_e64 v30, v30, v41, s[6:7]
	v_cndmask_b32_e64 v29, v29, v39, s[6:7]
	v_cndmask_b32_e64 v28, v28, v33, s[6:7]
	s_waitcnt vmcnt(0)
	v_pk_fma_f32 v[36:37], v[36:37], v[46:47], v[28:29]
	v_pk_fma_f32 v[34:35], v[34:35], v[48:49], v[30:31]

; __device__ __forceinline__ unsigned pk2(float lo, float hi) { f32x2 v = {lo, hi}; return __builtin_bit_cast(unsigned, __builtin_convertvector(v, bf16v2)); }
;   __device__ __forceinline__ void operator()(const Acc& acc, int brow, int bcol, int wr, int wc, int fr, int fq) const {
;     ...
;         const int r = brow + 128 * ai + 64 * wr + 16 * m + fr;
;         const float rstd = rsqrtf(RS[2 * r] * (1.f / 256.f) + 1e-6f) * QSCALE;
;         int b, key; row_bk(r, b, key);
;     ...
;             u32x2 o; o.x = pk2(v[0], v[1]); o.y = pk2(v[2], v[3]);
;             *(u32x2*)(qrow + (size_t)h * (NKEY * 96) + d32 + 16 * n) = o;
.LBB0_1138:
	v_cvt_pk_bf16_f32 v16, v16, v17
	v_cvt_pk_bf16_f32 v17, v18, v19
	v_add_u32_e32 v18, 0xb0, v173
	global_store_dwordx2 v[20:21], v[16:17], off offset:32
	v_lshlrev_b32_e32 v16, 1, v18
	v_ashrrev_i32_e32 v17, 31, v16
	v_lshl_add_u64 v[20:21], v[16:17], 2, s[16:17]
	v_mov_b32_e32 v17, v242
	v_cmp_lt_i32_e32 vcc, s67, v18
	s_and_saveexec_b64 s[0:1], vcc
	s_xor_b64 s[0:1], exec, s[0:1]
	s_cbranch_execz .LBB0_1140
	v_add_u32_e32 v19, 0xfffffcb0, v173
	s_waitcnt lgkmcnt(3)
	v_lshrrev_b32_e32 v22, 13, v19
	v_and_b32_e32 v19, 0x1fff, v19
	v_add_u32_e32 v132, 0x100, v19

;   __device__ __forceinline__ void operator()(const Acc& acc, int brow, int bcol, int wr, int wc, int fr, int fq) const {
;     ...
;         const float rstd = rsqrtf(RS[2 * r] * (1.f / 256.f) + 1e-6f) * QSCALE;
;         int b, key; row_bk(r, b, key);
;         const bool latent = r >= NCTX;
;         const int t = (r - NCTX) & 8191;
;         bf16_t* qrow = Qall + ((size_t)(b * 8) * NKEY + key) * 96 + 4 * fq;
; #pragma unroll
;         for (int bj = 0; bj < 2; ++bj) {
;           const int c32 = bcol + 128 * bj + 32 * wc;
;           const int h = c32 / 96, d32 = c32 - 96 * h;
; #pragma unroll
;           for (int n = 0; n < 2; ++n) {
;             f32x4 v = acc[ai][bj][m][n] * rstd;
;             if (d32 == 64) {
;               f32x4 pv;
; #pragma unroll
;               for (int j = 0; j < 4; ++j) pv[j] = __shfl_xor(v[j], 32);
;               if (latent) {
;                 const float* rp = rope + ((size_t)t * 2 + n) * 16 + 4 * (fq & 1);
;                 const f32x4 cs = *(const f32x4*)rp, sn = *(const f32x4*)(rp + 8);
;                 v = (fq < 2) ? (v * cs - pv * sn) : (pv * sn + v * cs);
.LBB0_1142:
	s_or_b64 exec, exec, s[0:1]
	v_fmamk_f32 v17, v17, 0x3b800000, v169
	v_mul_f32_e32 v19, 0x4b800000, v17
	v_cmp_gt_f32_e32 vcc, s68, v17
	v_cmp_lt_i32_e64 s[12:13], s67, v18
	v_add_u32_e32 v18, 0x3800, v16
	v_cndmask_b32_e32 v17, v17, v19, vcc
	v_rsq_f32_e32 v17, v17
	s_waitcnt lgkmcnt(1)
	v_and_b32_e32 v24, 0x3ffe, v18
	v_mul_f32_e32 v16, 0x45800000, v17
	v_cndmask_b32_e32 v16, v17, v16, vcc
	v_mul_f32_e32 v16, 0x3e16c740, v16
	v_pk_mul_f32 v[18:19], v[14:15], v[16:17] op_sel_hi:[1,0]
	s_and_b64 vcc, exec, s[8:9]
	v_pk_mul_f32 v[20:21], v[12:13], v[16:17] op_sel_hi:[1,0]
	s_cbranch_vccnz .LBB0_1146
	v_and_b32_e32 v13, 64, v172
	v_xor_b32_e32 v12, 32, v172
	v_add_u32_e32 v13, 64, v13
	v_cmp_lt_i32_e32 vcc, v12, v13
	s_nop 1
	v_cndmask_b32_e32 v12, v172, v12, vcc
	v_lshlrev_b32_e32 v15, 2, v12
	ds_bpermute_b32 v12, v15, v20
	ds_bpermute_b32 v13, v15, v21
	ds_bpermute_b32 v14, v15, v18
	ds_bpermute_b32 v15, v15, v19
	s_and_saveexec_b64 s[0:1], s[12:13]
	s_cbranch_execz .LBB0_1145
	v_lshlrev_b32_e32 v26, 6, v24
	s_waitcnt lgkmcnt(4)
	v_mov_b32_e32 v27, v133
	v_lshl_add_u64 v[30:31], v[140:141], 0, v[26:27]
	global_load_dwordx4 v[26:29], v[30:31], off offset:32
	s_nop 0
	global_load_dwordx4 v[30:33], v[30:31], off
	s_waitcnt vmcnt(1) lgkmcnt(0)
	v_pk_mul_f32 v[14:15], v[28:29], v[14:15]
	v_pk_mul_f32 v[12:13], v[26:27], v[12:13]
	v_xor_b32_e32 v25, 0x80000000, v14
	v_xor_b32_e32 v17, 0x80000000, v12
	v_xor_b32_e32 v23, 0x80000000, v13
	v_xor_b32_e32 v26, 0x80000000, v15
	v_cndmask_b32_e64 v15, v15, v26, s[6:7]
	v_cndmask_b32_e64 v14, v14, v25, s[6:7]
	v_cndmask_b32_e64 v13, v13, v23, s[6:7]
	v_cndmask_b32_e64 v12, v12, v17, s[6:7]
	s_waitcnt vmcnt(0)
	v_pk_fma_f32 v[20:21], v[20:21], v[30:31], v[12:13]
	v_pk_fma_f32 v[18:19], v[18:19], v[32:33], v[14:15]
